# SP2 loops in P13,P14 with first-iteration vmcnt waits skipped after an epilogue (prefetches already retired by the epilogue's vmcnt(0))
# speedup vs baseline: 1.0057x; 1.0057x over previous
.LBB0_1625:
	s_add_u32 s27, s10, 0x6e00000
	s_addc_u32 s28, s11, 0
	s_add_u32 s29, s10, 0x8e00000
	s_addc_u32 s33, s11, 0
	s_cmpk_lt_u32 s2, 0x100
	s_cselect_b32 s34, s33, 0
	s_cselect_b32 s35, s29, 0
	s_cmp_eq_u32 s31, 1
	s_cselect_b32 s37, s27, 0
	s_cselect_b32 s36, s28, 0
	s_add_u32 s35, s37, s35
	s_addc_u32 s34, s36, s34
	s_cmp_eq_u32 s31, 2
	s_cselect_b32 s36, s8, 0
	s_cselect_b32 s31, s9, 0
	s_add_u32 s35, s35, s36
	s_addc_u32 s31, s34, s31
	s_or_b32 s23, s23, s30
	s_lshl_b32 s23, s23, 1
	s_add_u32 s52, s35, s23
	s_addc_u32 s53, s31, 0
	s_add_u32 s64, s10, 0x2103000
	s_addc_u32 s65, s11, 0
	s_ashr_i32 s23, s22, 31
	s_lshl_b64 s[22:23], s[22:23], 2
	s_add_u32 s22, s64, s22
	s_addc_u32 s23, s65, s23
	s_lshl_b32 s30, s30, 2
	s_add_u32 s54, s22, s30
	s_addc_u32 s55, s23, 0
	s_mov_b64 s[22:23], 0x80
	v_lshl_add_u64 v[10:11], v[2:3], 0, s[22:23]
	s_add_i32 m0, s6, 0x18000
	s_mov_b64 s[34:35], 0x20080
	s_waitcnt vmcnt(2)
	s_mov_b32 s98, 0
	s_barrier
	global_load_lds_dwordx4 v[10:11], off
	v_lshl_add_u64 v[10:11], v[2:3], 0, s[34:35]
	s_add_i32 m0, s6, 0x1a000
	s_add_i32 s66, s6, 0x8000
	global_load_lds_dwordx4 v[10:11], off
	v_lshl_add_u64 v[10:11], v[4:5], 0, s[22:23]
	s_mov_b32 m0, s66
	s_add_i32 s67, s6, 0xa000
	global_load_lds_dwordx4 v[10:11], off
	v_lshl_add_u64 v[4:5], v[4:5], 0, s[34:35]
	s_mov_b32 m0, s67
	s_mov_b64 s[36:37], 0x40080
	global_load_lds_dwordx4 v[4:5], off
	v_lshl_add_u64 v[4:5], v[2:3], 0, s[36:37]
	s_add_i32 m0, s6, 0x1c000
	s_mov_b64 s[38:39], 0x60080
	global_load_lds_dwordx4 v[4:5], off
	v_lshl_add_u64 v[2:3], v[2:3], 0, s[38:39]
	s_add_i32 m0, s6, 0x1e000
	v_bfe_u32 v187, v6, 4, 2
	global_load_lds_dwordx4 v[2:3], off
	s_lshl_b32 s1, s1, 5
	v_and_b32_e32 v186, 15, v6
	v_lshlrev_b32_e32 v2, 4, v187
	v_lshlrev_b32_e32 v3, 2, v6
	s_and_b32 s69, s1, 0x60
	s_lshl_b32 s68, s18, 6
	v_lshl_or_b32 v2, v186, 6, v2
	s_lshl_b32 s18, s18, 13
	v_and_b32_e32 v3, 32, v3
	s_lshl_b32 s1, s69, 7
	v_bitop3_b32 v4, v2, s18, v3 bitop3:0xde
	v_bitop3_b32 v188, v2, s1, v3 bitop3:0xde
	v_lshlrev_b32_e32 v2, 14, v8
	v_and_b32_e32 v2, 0xffff8000, v2
	s_waitcnt vmcnt(6)
	s_cmpk_lt_u32 s0, 0x100
	v_lshl_add_u32 v2, v7, 11, v2
	v_and_b32_e32 v3, 1, v8
	s_cselect_b64 s[40:41], -1, 0
	v_lshl_or_b32 v2, v3, 6, v2
	s_add_i32 s72, 0, 0x10000
	s_add_i32 s73, 0, 0x14000
	s_mov_b32 s70, 0x18000
	s_mov_b32 s71, 0x8000
	v_lshl_add_u32 v166, v9, 1, v2
	v_mov_b32_e32 v167, v163
	v_add_u32_e32 v189, s72, v188
	v_add_u32_e32 v190, 0, v4
	v_add_u32_e32 v191, s73, v188
	s_lshl_b32 s18, s69, 1
	s_mov_b32 s74, 0x40000
	s_mov_b32 s75, 0x48000
	s_mov_b32 s76, 0x50000
	s_mov_b32 s77, 0x58000
	s_mov_b32 s78, s19
	s_barrier
	s_branch .LBB0_1628

.LBB0_1631:
	ds_read_b128 v[122:125], v189
	ds_read_b128 v[134:137], v189 offset:1024
	ds_read_b128 v[138:141], v189 offset:2048
	ds_read_b128 v[142:145], v189 offset:3072
	ds_read_b128 v[192:195], v191
	ds_read_b128 v[196:199], v191 offset:1024
	ds_read_b128 v[200:203], v191 offset:2048
	ds_read_b128 v[204:207], v191 offset:3072
	s_add_u32 s0, s60, 0xfffc0080
	s_addc_u32 s1, s61, -1
	s_cmp_eq_u32 s79, 12
	s_cselect_b32 s1, s57, s1
	s_cselect_b32 s0, s56, s0
	s_cselect_b32 s31, s59, s63
	s_cselect_b32 s30, s58, s62
	v_lshl_add_u64 v[252:253], s[60:61], 0, v[166:167]
	s_add_i32 m0, s6, 0xc000
	ds_read_b128 v[146:149], v190
	ds_read_b128 v[150:153], v190 offset:1024
	ds_read_b128 v[154:157], v190 offset:2048
	ds_read_b128 v[158:161], v190 offset:3072
	ds_read_b128 v[168:171], v190 offset:4096
	ds_read_b128 v[172:175], v190 offset:5120
	ds_read_b128 v[176:179], v190 offset:6144
	ds_read_b128 v[180:183], v190 offset:7168
	global_load_lds_dwordx4 v[252:253], off
	v_lshl_add_u64 v[252:253], v[252:253], 0, s[12:13]
	s_add_i32 m0, s6, 0xe000
	s_nop 0
	global_load_lds_dwordx4 v[252:253], off
	s_cmp_lg_u32 s98, 0
	s_cbranch_scc1 .Lsk1_p13
	s_waitcnt vmcnt(8)
.Lsk1_p13:
	s_waitcnt lgkmcnt(0)
	s_barrier
	s_setprio 1
	v_mfma_f32_16x16x32_bf16 v[130:133], v[122:125], v[146:149], v[130:133]
	v_mfma_f32_16x16x32_bf16 v[126:129], v[138:141], v[146:149], v[126:129]
	v_mfma_f32_16x16x32_bf16 v[118:121], v[122:125], v[154:157], v[118:121]
	v_mfma_f32_16x16x32_bf16 v[114:117], v[138:141], v[154:157], v[114:117]
	v_mfma_f32_16x16x32_bf16 v[110:113], v[122:125], v[168:171], v[110:113]
	v_mfma_f32_16x16x32_bf16 v[106:109], v[138:141], v[168:171], v[106:109]
	v_mfma_f32_16x16x32_bf16 v[102:105], v[122:125], v[176:179], v[102:105]
	v_mfma_f32_16x16x32_bf16 v[98:101], v[138:141], v[176:179], v[98:101]
	v_mfma_f32_16x16x32_bf16 v[130:133], v[134:137], v[150:153], v[130:133]
	v_mfma_f32_16x16x32_bf16 v[126:129], v[142:145], v[150:153], v[126:129]
	v_mfma_f32_16x16x32_bf16 v[118:121], v[134:137], v[158:161], v[118:121]
	v_mfma_f32_16x16x32_bf16 v[114:117], v[142:145], v[158:161], v[114:117]
	v_mfma_f32_16x16x32_bf16 v[110:113], v[134:137], v[172:175], v[110:113]
	v_mfma_f32_16x16x32_bf16 v[106:109], v[142:145], v[172:175], v[106:109]
	v_mfma_f32_16x16x32_bf16 v[102:105], v[134:137], v[180:183], v[102:105]
	v_mfma_f32_16x16x32_bf16 v[98:101], v[142:145], v[180:183], v[98:101]
	v_mfma_f32_16x16x32_bf16 v[62:65], v[192:195], v[146:149], v[62:65]
	v_mfma_f32_16x16x32_bf16 v[58:61], v[200:203], v[146:149], v[58:61]
	v_mfma_f32_16x16x32_bf16 v[54:57], v[192:195], v[154:157], v[54:57]
	v_mfma_f32_16x16x32_bf16 v[50:53], v[200:203], v[154:157], v[50:53]
	v_mfma_f32_16x16x32_bf16 v[46:49], v[192:195], v[168:171], v[46:49]
	v_mfma_f32_16x16x32_bf16 v[42:45], v[200:203], v[168:171], v[42:45]
	v_mfma_f32_16x16x32_bf16 v[38:41], v[192:195], v[176:179], v[38:41]
	v_mfma_f32_16x16x32_bf16 v[34:37], v[200:203], v[176:179], v[34:37]
	v_mfma_f32_16x16x32_bf16 v[62:65], v[196:199], v[150:153], v[62:65]
	v_mfma_f32_16x16x32_bf16 v[58:61], v[204:207], v[150:153], v[58:61]
	v_mfma_f32_16x16x32_bf16 v[54:57], v[196:199], v[158:161], v[54:57]
	v_mfma_f32_16x16x32_bf16 v[50:53], v[204:207], v[158:161], v[50:53]
	v_mfma_f32_16x16x32_bf16 v[46:49], v[196:199], v[172:175], v[46:49]
	v_mfma_f32_16x16x32_bf16 v[42:45], v[204:207], v[172:175], v[42:45]
	v_mfma_f32_16x16x32_bf16 v[38:41], v[196:199], v[180:183], v[38:41]
	v_mfma_f32_16x16x32_bf16 v[34:37], v[204:207], v[180:183], v[34:37]
	s_setprio 0
	s_barrier
	ds_read_b128 v[146:149], v190 offset:16384
	ds_read_b128 v[150:153], v190 offset:17408
	ds_read_b128 v[154:157], v190 offset:18432
	ds_read_b128 v[158:161], v190 offset:19456
	ds_read_b128 v[168:171], v190 offset:20480
	ds_read_b128 v[172:175], v190 offset:21504
	ds_read_b128 v[176:179], v190 offset:22528
	ds_read_b128 v[180:183], v190 offset:23552
	v_lshl_add_u64 v[208:209], s[0:1], 0, v[164:165]
	v_lshl_add_u64 v[184:185], s[30:31], 0, v[162:163]
	s_add_i32 s30, s72, s5
	s_mov_b32 m0, s30
	s_nop 0
	global_load_lds_dwordx4 v[184:185], off
	v_lshl_add_u64 v[210:211], v[184:185], 0, s[12:13]
	s_add_i32 m0, s30, 0x2000
	s_nop 0
	global_load_lds_dwordx4 v[210:211], off
	s_add_i32 s0, s73, s5
	v_lshl_add_u64 v[250:251], v[184:185], 0, s[14:15]
	s_mov_b32 m0, s0
	s_nop 0
	global_load_lds_dwordx4 v[250:251], off
	v_lshl_add_u64 v[250:251], v[184:185], 0, s[16:17]
	s_add_i32 m0, s0, 0x2000
	s_nop 0
	global_load_lds_dwordx4 v[250:251], off
	s_mov_b32 m0, s6
	s_nop 0
	global_load_lds_dwordx4 v[208:209], off
	v_lshl_add_u64 v[210:211], v[208:209], 0, s[12:13]
	s_mov_b32 m0, s7
	s_nop 0
	global_load_lds_dwordx4 v[210:211], off
	s_cmp_lg_u32 s98, 0
	s_cbranch_scc1 .Lsk2_p13
	s_waitcnt vmcnt(8)
.Lsk2_p13:
	s_mov_b32 s98, 0
	s_waitcnt lgkmcnt(0)
	s_barrier
	s_setprio 1
	v_mfma_f32_16x16x32_bf16 v[94:97], v[122:125], v[146:149], v[94:97]
	v_mfma_f32_16x16x32_bf16 v[90:93], v[138:141], v[146:149], v[90:93]
	v_mfma_f32_16x16x32_bf16 v[86:89], v[122:125], v[154:157], v[86:89]
	v_mfma_f32_16x16x32_bf16 v[82:85], v[138:141], v[154:157], v[82:85]
	v_mfma_f32_16x16x32_bf16 v[78:81], v[122:125], v[168:171], v[78:81]
	v_mfma_f32_16x16x32_bf16 v[74:77], v[138:141], v[168:171], v[74:77]
	v_mfma_f32_16x16x32_bf16 v[70:73], v[122:125], v[176:179], v[70:73]
	v_mfma_f32_16x16x32_bf16 v[66:69], v[138:141], v[176:179], v[66:69]
	v_mfma_f32_16x16x32_bf16 v[94:97], v[134:137], v[150:153], v[94:97]
	v_mfma_f32_16x16x32_bf16 v[90:93], v[142:145], v[150:153], v[90:93]
	v_mfma_f32_16x16x32_bf16 v[86:89], v[134:137], v[158:161], v[86:89]
	v_mfma_f32_16x16x32_bf16 v[82:85], v[142:145], v[158:161], v[82:85]
	v_mfma_f32_16x16x32_bf16 v[78:81], v[134:137], v[172:175], v[78:81]
	v_mfma_f32_16x16x32_bf16 v[74:77], v[142:145], v[172:175], v[74:77]
	v_mfma_f32_16x16x32_bf16 v[70:73], v[134:137], v[180:183], v[70:73]
	v_mfma_f32_16x16x32_bf16 v[66:69], v[142:145], v[180:183], v[66:69]
	v_mfma_f32_16x16x32_bf16 v[30:33], v[192:195], v[146:149], v[30:33]
	v_mfma_f32_16x16x32_bf16 v[26:29], v[200:203], v[146:149], v[26:29]
	v_mfma_f32_16x16x32_bf16 v[22:25], v[192:195], v[154:157], v[22:25]
	v_mfma_f32_16x16x32_bf16 v[18:21], v[200:203], v[154:157], v[18:21]
	v_mfma_f32_16x16x32_bf16 v[14:17], v[192:195], v[168:171], v[14:17]
	v_mfma_f32_16x16x32_bf16 v[10:13], v[200:203], v[168:171], v[10:13]
	v_mfma_f32_16x16x32_bf16 v[6:9], v[192:195], v[176:179], v[6:9]
	v_mfma_f32_16x16x32_bf16 v[2:5], v[200:203], v[176:179], v[2:5]
	v_mfma_f32_16x16x32_bf16 v[30:33], v[196:199], v[150:153], v[30:33]
	v_mfma_f32_16x16x32_bf16 v[26:29], v[204:207], v[150:153], v[26:29]
	v_mfma_f32_16x16x32_bf16 v[22:25], v[196:199], v[158:161], v[22:25]
	v_mfma_f32_16x16x32_bf16 v[18:21], v[204:207], v[158:161], v[18:21]
	v_mfma_f32_16x16x32_bf16 v[14:17], v[196:199], v[172:175], v[14:17]
	v_mfma_f32_16x16x32_bf16 v[10:13], v[204:207], v[172:175], v[10:13]
	v_mfma_f32_16x16x32_bf16 v[6:9], v[196:199], v[180:183], v[6:9]
	v_mfma_f32_16x16x32_bf16 v[2:5], v[204:207], v[180:183], v[2:5]
	s_setprio 0
	s_add_i32 s0, 0, 0x18000
	v_add_u32_e32 v142, s0, v188
	s_barrier
	s_add_i32 s1, 0, 0x1c000
	v_add_u32_e32 v204, s1, v188
	ds_read_b128 v[122:125], v142
	ds_read_b128 v[134:137], v142 offset:1024
	ds_read_b128 v[138:141], v142 offset:2048
	ds_read_b128 v[142:145], v142 offset:3072
	ds_read_b128 v[192:195], v204
	ds_read_b128 v[196:199], v204 offset:1024
	ds_read_b128 v[200:203], v204 offset:2048
	ds_read_b128 v[204:207], v204 offset:3072
	s_mov_b32 m0, s24
	v_lshl_add_u64 v[252:253], v[208:209], 0, s[14:15]
	ds_read_b128 v[146:149], v190 offset:32768
	ds_read_b128 v[150:153], v190 offset:33792
	ds_read_b128 v[154:157], v190 offset:34816
	ds_read_b128 v[158:161], v190 offset:35840
	ds_read_b128 v[168:171], v190 offset:36864
	ds_read_b128 v[172:175], v190 offset:37888
	ds_read_b128 v[176:179], v190 offset:38912
	ds_read_b128 v[180:183], v190 offset:39936
	global_load_lds_dwordx4 v[252:253], off
	v_lshl_add_u64 v[252:253], v[208:209], 0, s[16:17]
	s_mov_b32 m0, s25
	s_nop 0
	global_load_lds_dwordx4 v[252:253], off
	s_waitcnt vmcnt(8)
	s_waitcnt lgkmcnt(0)
	s_barrier
	s_setprio 1
	v_mfma_f32_16x16x32_bf16 v[130:133], v[122:125], v[146:149], v[130:133]
	v_mfma_f32_16x16x32_bf16 v[126:129], v[138:141], v[146:149], v[126:129]
	v_mfma_f32_16x16x32_bf16 v[118:121], v[122:125], v[154:157], v[118:121]
	v_mfma_f32_16x16x32_bf16 v[114:117], v[138:141], v[154:157], v[114:117]
	v_mfma_f32_16x16x32_bf16 v[110:113], v[122:125], v[168:171], v[110:113]
	v_mfma_f32_16x16x32_bf16 v[106:109], v[138:141], v[168:171], v[106:109]
	v_mfma_f32_16x16x32_bf16 v[102:105], v[122:125], v[176:179], v[102:105]
	v_mfma_f32_16x16x32_bf16 v[98:101], v[138:141], v[176:179], v[98:101]
	v_mfma_f32_16x16x32_bf16 v[130:133], v[134:137], v[150:153], v[130:133]
	v_mfma_f32_16x16x32_bf16 v[126:129], v[142:145], v[150:153], v[126:129]
	v_mfma_f32_16x16x32_bf16 v[118:121], v[134:137], v[158:161], v[118:121]
	v_mfma_f32_16x16x32_bf16 v[114:117], v[142:145], v[158:161], v[114:117]
	v_mfma_f32_16x16x32_bf16 v[110:113], v[134:137], v[172:175], v[110:113]
	v_mfma_f32_16x16x32_bf16 v[106:109], v[142:145], v[172:175], v[106:109]
	v_mfma_f32_16x16x32_bf16 v[102:105], v[134:137], v[180:183], v[102:105]
	v_mfma_f32_16x16x32_bf16 v[98:101], v[142:145], v[180:183], v[98:101]
	v_mfma_f32_16x16x32_bf16 v[62:65], v[192:195], v[146:149], v[62:65]
	v_mfma_f32_16x16x32_bf16 v[58:61], v[200:203], v[146:149], v[58:61]
	v_mfma_f32_16x16x32_bf16 v[54:57], v[192:195], v[154:157], v[54:57]
	v_mfma_f32_16x16x32_bf16 v[50:53], v[200:203], v[154:157], v[50:53]
	v_mfma_f32_16x16x32_bf16 v[46:49], v[192:195], v[168:171], v[46:49]
	v_mfma_f32_16x16x32_bf16 v[42:45], v[200:203], v[168:171], v[42:45]
	v_mfma_f32_16x16x32_bf16 v[38:41], v[192:195], v[176:179], v[38:41]
	v_mfma_f32_16x16x32_bf16 v[34:37], v[200:203], v[176:179], v[34:37]
	v_mfma_f32_16x16x32_bf16 v[62:65], v[196:199], v[150:153], v[62:65]
	v_mfma_f32_16x16x32_bf16 v[58:61], v[204:207], v[150:153], v[58:61]
	v_mfma_f32_16x16x32_bf16 v[54:57], v[196:199], v[158:161], v[54:57]
	v_mfma_f32_16x16x32_bf16 v[50:53], v[204:207], v[158:161], v[50:53]
	v_mfma_f32_16x16x32_bf16 v[46:49], v[196:199], v[172:175], v[46:49]
	v_mfma_f32_16x16x32_bf16 v[42:45], v[204:207], v[172:175], v[42:45]
	v_mfma_f32_16x16x32_bf16 v[38:41], v[196:199], v[180:183], v[38:41]
	v_mfma_f32_16x16x32_bf16 v[34:37], v[204:207], v[180:183], v[34:37]
	s_setprio 0
	s_barrier
	ds_read_b128 v[146:149], v190 offset:49152
	ds_read_b128 v[150:153], v190 offset:50176
	ds_read_b128 v[154:157], v190 offset:51200
	ds_read_b128 v[158:161], v190 offset:52224
	ds_read_b128 v[168:171], v190 offset:53248
	ds_read_b128 v[172:175], v190 offset:54272
	ds_read_b128 v[176:179], v190 offset:55296
	ds_read_b128 v[180:183], v190 offset:56320
	s_add_i32 s0, s0, s5
	v_lshl_add_u64 v[210:211], v[184:185], 0, s[22:23]
	s_mov_b32 m0, s0
	s_nop 0
	global_load_lds_dwordx4 v[210:211], off
	v_lshl_add_u64 v[210:211], v[184:185], 0, s[34:35]
	s_add_i32 m0, s0, 0x2000
	s_nop 0
	global_load_lds_dwordx4 v[210:211], off
	s_add_i32 s0, s1, s5
	v_lshl_add_u64 v[250:251], v[184:185], 0, s[36:37]
	s_mov_b32 m0, s0
	s_nop 0
	global_load_lds_dwordx4 v[250:251], off
	v_lshl_add_u64 v[250:251], v[184:185], 0, s[38:39]
	s_add_i32 m0, s0, 0x2000
	s_nop 0
	global_load_lds_dwordx4 v[250:251], off
	s_mov_b32 m0, s66
	v_lshl_add_u64 v[210:211], v[208:209], 0, s[22:23]
	global_load_lds_dwordx4 v[210:211], off
	v_lshl_add_u64 v[208:209], v[208:209], 0, s[34:35]
	s_mov_b32 m0, s67
	s_nop 0
	global_load_lds_dwordx4 v[208:209], off
	s_waitcnt vmcnt(8)
	s_waitcnt lgkmcnt(0)
	s_barrier
	s_setprio 1
	v_mfma_f32_16x16x32_bf16 v[94:97], v[122:125], v[146:149], v[94:97]
	v_mfma_f32_16x16x32_bf16 v[90:93], v[138:141], v[146:149], v[90:93]
	v_mfma_f32_16x16x32_bf16 v[86:89], v[122:125], v[154:157], v[86:89]
	v_mfma_f32_16x16x32_bf16 v[82:85], v[138:141], v[154:157], v[82:85]
	v_mfma_f32_16x16x32_bf16 v[78:81], v[122:125], v[168:171], v[78:81]
	v_mfma_f32_16x16x32_bf16 v[74:77], v[138:141], v[168:171], v[74:77]
	v_mfma_f32_16x16x32_bf16 v[70:73], v[122:125], v[176:179], v[70:73]
	v_mfma_f32_16x16x32_bf16 v[66:69], v[138:141], v[176:179], v[66:69]
	v_mfma_f32_16x16x32_bf16 v[94:97], v[134:137], v[150:153], v[94:97]
	v_mfma_f32_16x16x32_bf16 v[90:93], v[142:145], v[150:153], v[90:93]
	v_mfma_f32_16x16x32_bf16 v[86:89], v[134:137], v[158:161], v[86:89]
	v_mfma_f32_16x16x32_bf16 v[82:85], v[142:145], v[158:161], v[82:85]
	v_mfma_f32_16x16x32_bf16 v[78:81], v[134:137], v[172:175], v[78:81]
	v_mfma_f32_16x16x32_bf16 v[74:77], v[142:145], v[172:175], v[74:77]
	v_mfma_f32_16x16x32_bf16 v[70:73], v[134:137], v[180:183], v[70:73]
	v_mfma_f32_16x16x32_bf16 v[66:69], v[142:145], v[180:183], v[66:69]
	v_mfma_f32_16x16x32_bf16 v[30:33], v[192:195], v[146:149], v[30:33]
	v_mfma_f32_16x16x32_bf16 v[26:29], v[200:203], v[146:149], v[26:29]
	v_mfma_f32_16x16x32_bf16 v[22:25], v[192:195], v[154:157], v[22:25]
	v_mfma_f32_16x16x32_bf16 v[18:21], v[200:203], v[154:157], v[18:21]
	v_mfma_f32_16x16x32_bf16 v[14:17], v[192:195], v[168:171], v[14:17]
	v_mfma_f32_16x16x32_bf16 v[10:13], v[200:203], v[168:171], v[10:13]
	v_mfma_f32_16x16x32_bf16 v[6:9], v[192:195], v[176:179], v[6:9]
	v_mfma_f32_16x16x32_bf16 v[2:5], v[200:203], v[176:179], v[2:5]
	v_mfma_f32_16x16x32_bf16 v[30:33], v[196:199], v[150:153], v[30:33]
	v_mfma_f32_16x16x32_bf16 v[26:29], v[204:207], v[150:153], v[26:29]
	v_mfma_f32_16x16x32_bf16 v[22:25], v[196:199], v[158:161], v[22:25]
	v_mfma_f32_16x16x32_bf16 v[18:21], v[204:207], v[158:161], v[18:21]
	v_mfma_f32_16x16x32_bf16 v[14:17], v[196:199], v[172:175], v[14:17]
	v_mfma_f32_16x16x32_bf16 v[10:13], v[204:207], v[172:175], v[10:13]
	v_mfma_f32_16x16x32_bf16 v[6:9], v[196:199], v[180:183], v[6:9]
	v_mfma_f32_16x16x32_bf16 v[2:5], v[204:207], v[180:183], v[2:5]
	s_setprio 0
	s_add_i32 s79, s79, 2
	s_add_u32 s62, s62, 0x100
	s_addc_u32 s63, s63, 0
	s_add_u32 s60, s60, 0x100
	s_addc_u32 s61, s61, 0
	s_cmp_gt_u32 s79, 13
	s_barrier
	s_cbranch_scc0 .LBB0_1631
	s_mov_b32 s98, 1
	s_and_b64 vcc, exec, s[40:41]
	s_cbranch_vccz .LBB0_1634
	s_barrier

.LBB0_1696:
	s_add_u32 s26, s14, 0x1200000
	s_addc_u32 s27, s15, 0
	s_add_u32 s28, s14, 0x8e00000
	s_addc_u32 s29, s15, 0
	s_add_u32 s33, s14, 0x6e00000
	s_addc_u32 s64, s15, 0
	s_add_u32 s34, s12, 0x2000000
	s_addc_u32 s35, s13, 0
	s_add_u32 s36, s14, 0xce00000
	s_mov_b64 s[38:39], 0x80
	s_addc_u32 s37, s15, 0
	v_lshl_add_u64 v[10:11], v[2:3], 0, s[38:39]
	s_add_i32 m0, s6, 0x18000
	s_mov_b64 s[40:41], 0x20080
	s_waitcnt vmcnt(2)
	s_mov_b32 s98, 0
	s_barrier
	global_load_lds_dwordx4 v[10:11], off
	v_lshl_add_u64 v[10:11], v[2:3], 0, s[40:41]
	s_add_i32 m0, s6, 0x1a000
	s_add_i32 s65, s6, 0x8000
	global_load_lds_dwordx4 v[10:11], off
	v_lshl_add_u64 v[10:11], v[4:5], 0, s[38:39]
	s_mov_b32 m0, s65
	s_add_i32 s66, s6, 0xa000
	global_load_lds_dwordx4 v[10:11], off
	v_lshl_add_u64 v[4:5], v[4:5], 0, s[40:41]
	s_mov_b32 m0, s66
	s_mov_b64 s[42:43], 0x40080
	global_load_lds_dwordx4 v[4:5], off
	v_lshl_add_u64 v[4:5], v[2:3], 0, s[42:43]
	s_add_i32 m0, s6, 0x1c000
	s_mov_b64 s[44:45], 0x60080
	global_load_lds_dwordx4 v[4:5], off
	v_lshl_add_u64 v[2:3], v[2:3], 0, s[44:45]
	s_add_i32 m0, s6, 0x1e000
	v_bfe_u32 v211, v6, 4, 2
	global_load_lds_dwordx4 v[2:3], off
	s_lshl_b32 s1, s1, 5
	v_and_b32_e32 v210, 15, v6
	v_lshlrev_b32_e32 v2, 4, v211
	v_lshlrev_b32_e32 v3, 2, v6
	s_and_b32 s68, s1, 0x60
	s_lshl_b32 s67, s8, 6
	v_lshl_or_b32 v2, v210, 6, v2
	s_lshl_b32 s8, s8, 13
	v_and_b32_e32 v3, 32, v3
	s_lshl_b32 s1, s68, 7
	v_bitop3_b32 v4, v2, s8, v3 bitop3:0xde
	v_bitop3_b32 v212, v2, s1, v3 bitop3:0xde
	v_lshlrev_b32_e32 v2, 14, v7
	s_cmpk_lt_u32 s0, 0x100
	v_and_b32_e32 v2, 0xffff8000, v2
	s_waitcnt vmcnt(6)
	s_cselect_b64 s[46:47], -1, 0
	s_add_u32 s71, s14, 0x2106000
	v_lshl_add_u32 v2, v8, 11, v2
	v_and_b32_e32 v3, 1, v7
	s_addc_u32 s72, s15, 0
	v_lshl_or_b32 v2, v3, 6, v2
	s_add_i32 s73, 0, 0x10000
	s_add_i32 s74, 0, 0x14000
	s_mov_b32 s69, 0x18000
	s_mov_b32 s70, 0x8000
	v_lshl_add_u32 v198, v9, 1, v2
	v_mov_b32_e32 v199, v197
	v_add_u32_e32 v213, s73, v212
	v_add_u32_e32 v214, 0, v4
	v_add_u32_e32 v215, s74, v212
	s_mov_b32 s75, 0x40000
	s_mov_b32 s76, 0x48000
	s_mov_b32 s77, 0x50000
	s_mov_b32 s78, 0x58000
	s_mov_b32 s79, 0x42a00000
	s_mov_b32 s85, 0
	s_mov_b32 s81, 0
	s_barrier
	s_branch .LBB0_1699

.LBB0_1706:
	ds_read_b128 v[130:133], v213
	ds_read_b128 v[134:137], v213 offset:1024
	ds_read_b128 v[138:141], v213 offset:2048
	ds_read_b128 v[142:145], v213 offset:3072
	ds_read_b128 v[178:181], v215
	ds_read_b128 v[182:185], v215 offset:1024
	ds_read_b128 v[186:189], v215 offset:2048
	ds_read_b128 v[190:193], v215 offset:3072
	s_add_u32 s0, s60, 0xfffc0080
	s_addc_u32 s1, s61, -1
	s_cmp_eq_u32 s86, 12
	s_cselect_b32 s1, s9, s1
	s_cselect_b32 s0, s8, s0
	s_cselect_b32 s31, s59, s63
	s_cselect_b32 s30, s58, s62
	v_lshl_add_u64 v[252:253], s[60:61], 0, v[198:199]
	s_add_i32 m0, s6, 0xc000
	ds_read_b128 v[146:149], v214
	ds_read_b128 v[150:153], v214 offset:1024
	ds_read_b128 v[154:157], v214 offset:2048
	ds_read_b128 v[158:161], v214 offset:3072
	ds_read_b128 v[162:165], v214 offset:4096
	ds_read_b128 v[166:169], v214 offset:5120
	ds_read_b128 v[170:173], v214 offset:6144
	ds_read_b128 v[174:177], v214 offset:7168
	global_load_lds_dwordx4 v[252:253], off
	v_lshl_add_u64 v[252:253], v[252:253], 0, s[10:11]
	s_add_i32 m0, s6, 0xe000
	s_nop 0
	global_load_lds_dwordx4 v[252:253], off
	s_cmp_lg_u32 s98, 0
	s_cbranch_scc1 .Lsk1_p14
	s_waitcnt vmcnt(8)
.Lsk1_p14:
	s_waitcnt lgkmcnt(0)
	s_barrier
	s_setprio 1
	v_mfma_f32_16x16x32_bf16 v[126:129], v[130:133], v[146:149], v[126:129]
	v_mfma_f32_16x16x32_bf16 v[122:125], v[138:141], v[146:149], v[122:125]
	v_mfma_f32_16x16x32_bf16 v[118:121], v[130:133], v[154:157], v[118:121]
	v_mfma_f32_16x16x32_bf16 v[114:117], v[138:141], v[154:157], v[114:117]
	v_mfma_f32_16x16x32_bf16 v[110:113], v[130:133], v[162:165], v[110:113]
	v_mfma_f32_16x16x32_bf16 v[106:109], v[138:141], v[162:165], v[106:109]
	v_mfma_f32_16x16x32_bf16 v[102:105], v[130:133], v[170:173], v[102:105]
	v_mfma_f32_16x16x32_bf16 v[98:101], v[138:141], v[170:173], v[98:101]
	v_mfma_f32_16x16x32_bf16 v[126:129], v[134:137], v[150:153], v[126:129]
	v_mfma_f32_16x16x32_bf16 v[122:125], v[142:145], v[150:153], v[122:125]
	v_mfma_f32_16x16x32_bf16 v[118:121], v[134:137], v[158:161], v[118:121]
	v_mfma_f32_16x16x32_bf16 v[114:117], v[142:145], v[158:161], v[114:117]
	v_mfma_f32_16x16x32_bf16 v[110:113], v[134:137], v[166:169], v[110:113]
	v_mfma_f32_16x16x32_bf16 v[106:109], v[142:145], v[166:169], v[106:109]
	v_mfma_f32_16x16x32_bf16 v[102:105], v[134:137], v[174:177], v[102:105]
	v_mfma_f32_16x16x32_bf16 v[98:101], v[142:145], v[174:177], v[98:101]
	v_mfma_f32_16x16x32_bf16 v[62:65], v[178:181], v[146:149], v[62:65]
	v_mfma_f32_16x16x32_bf16 v[58:61], v[186:189], v[146:149], v[58:61]
	v_mfma_f32_16x16x32_bf16 v[54:57], v[178:181], v[154:157], v[54:57]
	v_mfma_f32_16x16x32_bf16 v[50:53], v[186:189], v[154:157], v[50:53]
	v_mfma_f32_16x16x32_bf16 v[46:49], v[178:181], v[162:165], v[46:49]
	v_mfma_f32_16x16x32_bf16 v[42:45], v[186:189], v[162:165], v[42:45]
	v_mfma_f32_16x16x32_bf16 v[38:41], v[178:181], v[170:173], v[38:41]
	v_mfma_f32_16x16x32_bf16 v[34:37], v[186:189], v[170:173], v[34:37]
	v_mfma_f32_16x16x32_bf16 v[62:65], v[182:185], v[150:153], v[62:65]
	v_mfma_f32_16x16x32_bf16 v[58:61], v[190:193], v[150:153], v[58:61]
	v_mfma_f32_16x16x32_bf16 v[54:57], v[182:185], v[158:161], v[54:57]
	v_mfma_f32_16x16x32_bf16 v[50:53], v[190:193], v[158:161], v[50:53]
	v_mfma_f32_16x16x32_bf16 v[46:49], v[182:185], v[166:169], v[46:49]
	v_mfma_f32_16x16x32_bf16 v[42:45], v[190:193], v[166:169], v[42:45]
	v_mfma_f32_16x16x32_bf16 v[38:41], v[182:185], v[174:177], v[38:41]
	v_mfma_f32_16x16x32_bf16 v[34:37], v[190:193], v[174:177], v[34:37]
	s_setprio 0
	s_barrier
	ds_read_b128 v[146:149], v214 offset:16384
	ds_read_b128 v[150:153], v214 offset:17408
	ds_read_b128 v[154:157], v214 offset:18432
	ds_read_b128 v[158:161], v214 offset:19456
	ds_read_b128 v[162:165], v214 offset:20480
	ds_read_b128 v[166:169], v214 offset:21504
	ds_read_b128 v[170:173], v214 offset:22528
	ds_read_b128 v[174:177], v214 offset:23552
	v_lshl_add_u64 v[202:203], s[0:1], 0, v[194:195]
	v_lshl_add_u64 v[200:201], s[30:31], 0, v[196:197]
	s_add_i32 s30, s73, s5
	s_mov_b32 m0, s30
	s_nop 0
	global_load_lds_dwordx4 v[200:201], off
	v_lshl_add_u64 v[204:205], v[200:201], 0, s[10:11]
	s_add_i32 m0, s30, 0x2000
	s_nop 0
	global_load_lds_dwordx4 v[204:205], off
	s_add_i32 s0, s74, s5
	v_lshl_add_u64 v[250:251], v[200:201], 0, s[16:17]
	s_mov_b32 m0, s0
	s_nop 0
	global_load_lds_dwordx4 v[250:251], off
	v_lshl_add_u64 v[250:251], v[200:201], 0, s[18:19]
	s_add_i32 m0, s0, 0x2000
	s_nop 0
	global_load_lds_dwordx4 v[250:251], off
	s_mov_b32 m0, s6
	s_nop 0
	global_load_lds_dwordx4 v[202:203], off
	v_lshl_add_u64 v[204:205], v[202:203], 0, s[10:11]
	s_mov_b32 m0, s7
	s_nop 0
	global_load_lds_dwordx4 v[204:205], off
	s_cmp_lg_u32 s98, 0
	s_cbranch_scc1 .Lsk2_p14
	s_waitcnt vmcnt(8)
.Lsk2_p14:
	s_mov_b32 s98, 0
	s_waitcnt lgkmcnt(0)
	s_barrier
	s_setprio 1
	v_mfma_f32_16x16x32_bf16 v[94:97], v[130:133], v[146:149], v[94:97]
	v_mfma_f32_16x16x32_bf16 v[90:93], v[138:141], v[146:149], v[90:93]
	v_mfma_f32_16x16x32_bf16 v[86:89], v[130:133], v[154:157], v[86:89]
	v_mfma_f32_16x16x32_bf16 v[82:85], v[138:141], v[154:157], v[82:85]
	v_mfma_f32_16x16x32_bf16 v[78:81], v[130:133], v[162:165], v[78:81]
	v_mfma_f32_16x16x32_bf16 v[74:77], v[138:141], v[162:165], v[74:77]
	v_mfma_f32_16x16x32_bf16 v[70:73], v[130:133], v[170:173], v[70:73]
	v_mfma_f32_16x16x32_bf16 v[66:69], v[138:141], v[170:173], v[66:69]
	v_mfma_f32_16x16x32_bf16 v[94:97], v[134:137], v[150:153], v[94:97]
	v_mfma_f32_16x16x32_bf16 v[90:93], v[142:145], v[150:153], v[90:93]
	v_mfma_f32_16x16x32_bf16 v[86:89], v[134:137], v[158:161], v[86:89]
	v_mfma_f32_16x16x32_bf16 v[82:85], v[142:145], v[158:161], v[82:85]
	v_mfma_f32_16x16x32_bf16 v[78:81], v[134:137], v[166:169], v[78:81]
	v_mfma_f32_16x16x32_bf16 v[74:77], v[142:145], v[166:169], v[74:77]
	v_mfma_f32_16x16x32_bf16 v[70:73], v[134:137], v[174:177], v[70:73]
	v_mfma_f32_16x16x32_bf16 v[66:69], v[142:145], v[174:177], v[66:69]
	v_mfma_f32_16x16x32_bf16 v[30:33], v[178:181], v[146:149], v[30:33]
	v_mfma_f32_16x16x32_bf16 v[26:29], v[186:189], v[146:149], v[26:29]
	v_mfma_f32_16x16x32_bf16 v[22:25], v[178:181], v[154:157], v[22:25]
	v_mfma_f32_16x16x32_bf16 v[18:21], v[186:189], v[154:157], v[18:21]
	v_mfma_f32_16x16x32_bf16 v[14:17], v[178:181], v[162:165], v[14:17]
	v_mfma_f32_16x16x32_bf16 v[10:13], v[186:189], v[162:165], v[10:13]
	v_mfma_f32_16x16x32_bf16 v[6:9], v[178:181], v[170:173], v[6:9]
	v_mfma_f32_16x16x32_bf16 v[2:5], v[186:189], v[170:173], v[2:5]
	v_mfma_f32_16x16x32_bf16 v[30:33], v[182:185], v[150:153], v[30:33]
	v_mfma_f32_16x16x32_bf16 v[26:29], v[190:193], v[150:153], v[26:29]
	v_mfma_f32_16x16x32_bf16 v[22:25], v[182:185], v[158:161], v[22:25]
	v_mfma_f32_16x16x32_bf16 v[18:21], v[190:193], v[158:161], v[18:21]
	v_mfma_f32_16x16x32_bf16 v[14:17], v[182:185], v[166:169], v[14:17]
	v_mfma_f32_16x16x32_bf16 v[10:13], v[190:193], v[166:169], v[10:13]
	v_mfma_f32_16x16x32_bf16 v[6:9], v[182:185], v[174:177], v[6:9]
	v_mfma_f32_16x16x32_bf16 v[2:5], v[190:193], v[174:177], v[2:5]
	s_setprio 0
	s_add_i32 s0, 0, 0x18000
	v_add_u32_e32 v142, s0, v212
	s_barrier
	s_add_i32 s1, 0, 0x1c000
	v_add_u32_e32 v190, s1, v212
	ds_read_b128 v[130:133], v142
	ds_read_b128 v[134:137], v142 offset:1024
	ds_read_b128 v[138:141], v142 offset:2048
	ds_read_b128 v[142:145], v142 offset:3072
	ds_read_b128 v[178:181], v190
	ds_read_b128 v[182:185], v190 offset:1024
	ds_read_b128 v[186:189], v190 offset:2048
	ds_read_b128 v[190:193], v190 offset:3072
	s_mov_b32 m0, s24
	v_lshl_add_u64 v[252:253], v[202:203], 0, s[16:17]
	ds_read_b128 v[146:149], v214 offset:32768
	ds_read_b128 v[150:153], v214 offset:33792
	ds_read_b128 v[154:157], v214 offset:34816
	ds_read_b128 v[158:161], v214 offset:35840
	ds_read_b128 v[162:165], v214 offset:36864
	ds_read_b128 v[166:169], v214 offset:37888
	ds_read_b128 v[170:173], v214 offset:38912
	ds_read_b128 v[174:177], v214 offset:39936
	global_load_lds_dwordx4 v[252:253], off
	v_lshl_add_u64 v[252:253], v[202:203], 0, s[18:19]
	s_mov_b32 m0, s25
	s_nop 0
	global_load_lds_dwordx4 v[252:253], off
	s_waitcnt vmcnt(8)
	s_waitcnt lgkmcnt(0)
	s_barrier
	s_setprio 1
	v_mfma_f32_16x16x32_bf16 v[126:129], v[130:133], v[146:149], v[126:129]
	v_mfma_f32_16x16x32_bf16 v[122:125], v[138:141], v[146:149], v[122:125]
	v_mfma_f32_16x16x32_bf16 v[118:121], v[130:133], v[154:157], v[118:121]
	v_mfma_f32_16x16x32_bf16 v[114:117], v[138:141], v[154:157], v[114:117]
	v_mfma_f32_16x16x32_bf16 v[110:113], v[130:133], v[162:165], v[110:113]
	v_mfma_f32_16x16x32_bf16 v[106:109], v[138:141], v[162:165], v[106:109]
	v_mfma_f32_16x16x32_bf16 v[102:105], v[130:133], v[170:173], v[102:105]
	v_mfma_f32_16x16x32_bf16 v[98:101], v[138:141], v[170:173], v[98:101]
	v_mfma_f32_16x16x32_bf16 v[126:129], v[134:137], v[150:153], v[126:129]
	v_mfma_f32_16x16x32_bf16 v[122:125], v[142:145], v[150:153], v[122:125]
	v_mfma_f32_16x16x32_bf16 v[118:121], v[134:137], v[158:161], v[118:121]
	v_mfma_f32_16x16x32_bf16 v[114:117], v[142:145], v[158:161], v[114:117]
	v_mfma_f32_16x16x32_bf16 v[110:113], v[134:137], v[166:169], v[110:113]
	v_mfma_f32_16x16x32_bf16 v[106:109], v[142:145], v[166:169], v[106:109]
	v_mfma_f32_16x16x32_bf16 v[102:105], v[134:137], v[174:177], v[102:105]
	v_mfma_f32_16x16x32_bf16 v[98:101], v[142:145], v[174:177], v[98:101]
	v_mfma_f32_16x16x32_bf16 v[62:65], v[178:181], v[146:149], v[62:65]
	v_mfma_f32_16x16x32_bf16 v[58:61], v[186:189], v[146:149], v[58:61]
	v_mfma_f32_16x16x32_bf16 v[54:57], v[178:181], v[154:157], v[54:57]
	v_mfma_f32_16x16x32_bf16 v[50:53], v[186:189], v[154:157], v[50:53]
	v_mfma_f32_16x16x32_bf16 v[46:49], v[178:181], v[162:165], v[46:49]
	v_mfma_f32_16x16x32_bf16 v[42:45], v[186:189], v[162:165], v[42:45]
	v_mfma_f32_16x16x32_bf16 v[38:41], v[178:181], v[170:173], v[38:41]
	v_mfma_f32_16x16x32_bf16 v[34:37], v[186:189], v[170:173], v[34:37]
	v_mfma_f32_16x16x32_bf16 v[62:65], v[182:185], v[150:153], v[62:65]
	v_mfma_f32_16x16x32_bf16 v[58:61], v[190:193], v[150:153], v[58:61]
	v_mfma_f32_16x16x32_bf16 v[54:57], v[182:185], v[158:161], v[54:57]
	v_mfma_f32_16x16x32_bf16 v[50:53], v[190:193], v[158:161], v[50:53]
	v_mfma_f32_16x16x32_bf16 v[46:49], v[182:185], v[166:169], v[46:49]
	v_mfma_f32_16x16x32_bf16 v[42:45], v[190:193], v[166:169], v[42:45]
	v_mfma_f32_16x16x32_bf16 v[38:41], v[182:185], v[174:177], v[38:41]
	v_mfma_f32_16x16x32_bf16 v[34:37], v[190:193], v[174:177], v[34:37]
	s_setprio 0
	s_barrier
	ds_read_b128 v[146:149], v214 offset:49152
	ds_read_b128 v[150:153], v214 offset:50176
	ds_read_b128 v[154:157], v214 offset:51200
	ds_read_b128 v[158:161], v214 offset:52224
	ds_read_b128 v[162:165], v214 offset:53248
	ds_read_b128 v[166:169], v214 offset:54272
	ds_read_b128 v[170:173], v214 offset:55296
	ds_read_b128 v[174:177], v214 offset:56320
	s_add_i32 s0, s0, s5
	v_lshl_add_u64 v[204:205], v[200:201], 0, s[38:39]
	s_mov_b32 m0, s0
	s_nop 0
	global_load_lds_dwordx4 v[204:205], off
	v_lshl_add_u64 v[204:205], v[200:201], 0, s[40:41]
	s_add_i32 m0, s0, 0x2000
	s_nop 0
	global_load_lds_dwordx4 v[204:205], off
	s_add_i32 s0, s1, s5
	v_lshl_add_u64 v[250:251], v[200:201], 0, s[42:43]
	s_mov_b32 m0, s0
	s_nop 0
	global_load_lds_dwordx4 v[250:251], off
	v_lshl_add_u64 v[250:251], v[200:201], 0, s[44:45]
	s_add_i32 m0, s0, 0x2000
	s_nop 0
	global_load_lds_dwordx4 v[250:251], off
	s_mov_b32 m0, s65
	v_lshl_add_u64 v[204:205], v[202:203], 0, s[38:39]
	global_load_lds_dwordx4 v[204:205], off
	v_lshl_add_u64 v[202:203], v[202:203], 0, s[40:41]
	s_mov_b32 m0, s66
	s_nop 0
	global_load_lds_dwordx4 v[202:203], off
	s_waitcnt vmcnt(8)
	s_waitcnt lgkmcnt(0)
	s_barrier
	s_setprio 1
	v_mfma_f32_16x16x32_bf16 v[94:97], v[130:133], v[146:149], v[94:97]
	v_mfma_f32_16x16x32_bf16 v[90:93], v[138:141], v[146:149], v[90:93]
	v_mfma_f32_16x16x32_bf16 v[86:89], v[130:133], v[154:157], v[86:89]
	v_mfma_f32_16x16x32_bf16 v[82:85], v[138:141], v[154:157], v[82:85]
	v_mfma_f32_16x16x32_bf16 v[78:81], v[130:133], v[162:165], v[78:81]
	v_mfma_f32_16x16x32_bf16 v[74:77], v[138:141], v[162:165], v[74:77]
	v_mfma_f32_16x16x32_bf16 v[70:73], v[130:133], v[170:173], v[70:73]
	v_mfma_f32_16x16x32_bf16 v[66:69], v[138:141], v[170:173], v[66:69]
	v_mfma_f32_16x16x32_bf16 v[94:97], v[134:137], v[150:153], v[94:97]
	v_mfma_f32_16x16x32_bf16 v[90:93], v[142:145], v[150:153], v[90:93]
	v_mfma_f32_16x16x32_bf16 v[86:89], v[134:137], v[158:161], v[86:89]
	v_mfma_f32_16x16x32_bf16 v[82:85], v[142:145], v[158:161], v[82:85]
	v_mfma_f32_16x16x32_bf16 v[78:81], v[134:137], v[166:169], v[78:81]
	v_mfma_f32_16x16x32_bf16 v[74:77], v[142:145], v[166:169], v[74:77]
	v_mfma_f32_16x16x32_bf16 v[70:73], v[134:137], v[174:177], v[70:73]
	v_mfma_f32_16x16x32_bf16 v[66:69], v[142:145], v[174:177], v[66:69]
	v_mfma_f32_16x16x32_bf16 v[30:33], v[178:181], v[146:149], v[30:33]
	v_mfma_f32_16x16x32_bf16 v[26:29], v[186:189], v[146:149], v[26:29]
	v_mfma_f32_16x16x32_bf16 v[22:25], v[178:181], v[154:157], v[22:25]
	v_mfma_f32_16x16x32_bf16 v[18:21], v[186:189], v[154:157], v[18:21]
	v_mfma_f32_16x16x32_bf16 v[14:17], v[178:181], v[162:165], v[14:17]
	v_mfma_f32_16x16x32_bf16 v[10:13], v[186:189], v[162:165], v[10:13]
	v_mfma_f32_16x16x32_bf16 v[6:9], v[178:181], v[170:173], v[6:9]
	v_mfma_f32_16x16x32_bf16 v[2:5], v[186:189], v[170:173], v[2:5]
	v_mfma_f32_16x16x32_bf16 v[30:33], v[182:185], v[150:153], v[30:33]
	v_mfma_f32_16x16x32_bf16 v[26:29], v[190:193], v[150:153], v[26:29]
	v_mfma_f32_16x16x32_bf16 v[22:25], v[182:185], v[158:161], v[22:25]
	v_mfma_f32_16x16x32_bf16 v[18:21], v[190:193], v[158:161], v[18:21]
	v_mfma_f32_16x16x32_bf16 v[14:17], v[182:185], v[166:169], v[14:17]
	v_mfma_f32_16x16x32_bf16 v[10:13], v[190:193], v[166:169], v[10:13]
	v_mfma_f32_16x16x32_bf16 v[6:9], v[182:185], v[174:177], v[6:9]
	v_mfma_f32_16x16x32_bf16 v[2:5], v[190:193], v[174:177], v[2:5]
	s_setprio 0
	s_add_i32 s86, s86, 2
	s_add_u32 s62, s62, 0x100
	s_addc_u32 s63, s63, 0
	s_add_u32 s60, s60, 0x100
	s_addc_u32 s61, s61, 0
	s_cmp_gt_u32 s86, 13
	s_barrier
	s_cbranch_scc0 .LBB0_1706
	s_mov_b32 s98, 1
	s_and_b64 vcc, exec, s[46:47]
	s_cbranch_vccz .LBB0_1709
	s_barrier

	.amdhsa_kernel _Z6mk_fwdILj262143EEv6Params
		.amdhsa_group_segment_fixed_size 0
		.amdhsa_private_segment_fixed_size 0
		.amdhsa_kernarg_size 496
		.amdhsa_user_sgpr_count 2
		.amdhsa_user_sgpr_dispatch_ptr 0
		.amdhsa_user_sgpr_queue_ptr 0
		.amdhsa_user_sgpr_kernarg_segment_ptr 1
		.amdhsa_user_sgpr_dispatch_id 0
		.amdhsa_user_sgpr_kernarg_preload_length 0
		.amdhsa_user_sgpr_kernarg_preload_offset 0
		.amdhsa_user_sgpr_private_segment_size 0
		.amdhsa_uses_dynamic_stack 0
		.amdhsa_enable_private_segment 0
		.amdhsa_system_sgpr_workgroup_id_x 1
		.amdhsa_system_sgpr_workgroup_id_y 0
		.amdhsa_system_sgpr_workgroup_id_z 0
		.amdhsa_system_sgpr_workgroup_info 0
		.amdhsa_system_vgpr_workitem_id 0
		.amdhsa_next_free_vgpr 255
		.amdhsa_next_free_sgpr 102
		.amdhsa_accum_offset 256
		.amdhsa_reserve_vcc 1
		.amdhsa_float_round_mode_32 0
		.amdhsa_float_round_mode_16_64 0
		.amdhsa_float_denorm_mode_32 3
		.amdhsa_float_denorm_mode_16_64 3
		.amdhsa_dx10_clamp 1
		.amdhsa_ieee_mode 1
		.amdhsa_fp16_overflow 0
		.amdhsa_tg_split 0
		.amdhsa_exception_fp_ieee_invalid_op 0
		.amdhsa_exception_fp_denorm_src 0
		.amdhsa_exception_fp_ieee_div_zero 0
		.amdhsa_exception_fp_ieee_overflow 0
		.amdhsa_exception_fp_ieee_underflow 0
		.amdhsa_exception_fp_ieee_inexact 0
		.amdhsa_exception_int_div_zero 0
	.end_amdhsa_kernel

amdhsa.kernels:
  - .agpr_count:     0
    .args:
      - .offset:         0
        .size:           240
        .value_kind:     by_value
      - .offset:         240
        .size:           4
        .value_kind:     hidden_block_count_x
      - .offset:         244
        .size:           4
        .value_kind:     hidden_block_count_y
      - .offset:         248
        .size:           4
        .value_kind:     hidden_block_count_z
      - .offset:         252
        .size:           2
        .value_kind:     hidden_group_size_x
      - .offset:         254
        .size:           2
        .value_kind:     hidden_group_size_y
      - .offset:         256
        .size:           2
        .value_kind:     hidden_group_size_z
      - .offset:         258
        .size:           2
        .value_kind:     hidden_remainder_x
      - .offset:         260
        .size:           2
        .value_kind:     hidden_remainder_y
      - .offset:         262
        .size:           2
        .value_kind:     hidden_remainder_z
      - .offset:         280
        .size:           8
        .value_kind:     hidden_global_offset_x
      - .offset:         288
        .size:           8
        .value_kind:     hidden_global_offset_y
      - .offset:         296
        .size:           8
        .value_kind:     hidden_global_offset_z
      - .offset:         304
        .size:           2
        .value_kind:     hidden_grid_dims
      - .offset:         360
        .size:           4
        .value_kind:     hidden_dynamic_lds_size
    .group_segment_fixed_size: 0
    .kernarg_segment_align: 8
    .kernarg_segment_size: 496
    .language:       OpenCL C
    .language_version:
      - 2
      - 0
    .max_flat_workgroup_size: 512
    .name:           _Z6mk_fwdILj262143EEv6Params
    .private_segment_fixed_size: 0
    .sgpr_count:     108
    .sgpr_spill_count: 30
    .symbol:         _Z6mk_fwdILj262143EEv6Params.kd
    .uniform_work_group_size: 1
    .uses_dynamic_stack: false
    .vgpr_count:     255
    .vgpr_spill_count: 0
    .wavefront_size: 64
